# SGU workgroups start their item list ~2us late (s_sleep) so the ctx GEMM gets an uncontended start
# speedup vs baseline: 1.0026x; 1.0026x over previous
; #define LAS __attribute__((address_space(3)))
; __device__ __forceinline__ int opaque_tid() { int t = threadIdx.x; asm volatile("" : "+v"(t)); return t; }
; __device__ __forceinline__ void sgu_list(LAS unsigned char* lds, const Params& P, int i0, int istride) {
;     const int tid = opaque_tid(), lane = tid & 63, wid = __builtin_amdgcn_readfirstlane(tid >> 6);
;     if (i0 >= 1024) return;
;     LAS unsigned char* VT = lds;
;     LAS unsigned char* UG = lds + 128 * VT_PITCH;
;     LAS float* ST = (LAS float*)(lds + 2 * 128 * VT_PITCH);
;     bf16_t* Z = (bf16_t*)(P.ws + WS_Z); const bf16_t* SguW = (const bf16_t*)(P.ws + WS_SGUW);
;     SguRegs R;
;     sgu_load(R, P, Z, (size_t)(i0 >> 7) * SEQ + ((i0 >> 3) & 15) * 128, i0 & 7, tid);
;     const int cp = tid & 63, tg = tid >> 6, c0 = 2 * cp;
;     const int rr = tid >> 4, cc = (tid & 15) * 8;
;     const int pb = wid & 3, cb0 = (wid >> 2) * 2, ml = lane & 31, kh = lane >> 5;
;     for (int i = i0; i < 1024; i += istride) {
; __global__ void __launch_bounds__(NTHREADS, 2) fwd_megakernel(Params P) {
;     ...
;         const int G = (int)gridDim.x, bx = (int)blockIdx.x, ctxB = G < 32 ? G : 32;
;         if (bx < ctxB) {
;             pg8::Gemm g{(const bf16_t*)(P.ws + WS_HN) + (size_t)MROWS * DM, (const bf16_t*)(P.ws + WS_WINT), DM, DM, 256};
;             pg8::StaticOrder S; S.init(CROWS, DM, ctxB, bx);
;             pg8::EpiCtx EC{pg8::EpiInProj{(bf16_t*)(P.ws + WS_Z), (bf16_t*)(P.ws + WS_ZC), (float*)(P.ws + WS_STATS)}};
;             pg8::gemm_phase<pg8::EpiCtx, pg8::StaticOrder>(lds, g, S, EC);
;             __syncthreads();
;             if (threadIdx.x == 0) {
;                 __hip_atomic_fetch_add((unsigned*)(P.ws + WS_CTX_CNT), 1u, __ATOMIC_RELAXED, __HIP_MEMORY_SCOPE_AGENT); }
;             if (G <= ctxB) sgu_list(lds, P, bx, G);
;         } else sgu_list(lds, P, bx - ctxB, G - ctxB);
.LBB0_226:
	v_readlane_b32 s4, v255, 0
	s_cmp_lt_i32 s4, 4
	s_cselect_b64 s[2:3], -1, 0
	s_and_b64 s[10:11], s[2:3], s[0:1]
	s_andn2_b64 vcc, exec, s[10:11]
	v_readlane_b32 s5, v255, 1
	v_readlane_b32 s6, v255, 2
	v_readlane_b32 s7, v255, 3
	s_cbranch_vccnz .LBB0_318
	s_min_i32 s2, s34, 32
	v_writelane_b32 v255, s10, 16
	s_cmp_ge_i32 s24, s2
	s_mov_b64 s[0:1], -1
	v_writelane_b32 v255, s11, 17
	s_cbranch_scc0 .LBB0_237
	v_mov_b32_e32 v44, v167
	s_sub_i32 s0, s24, s2
	s_cmpk_gt_i32 s0, 0x3ff
	v_ashrrev_i32_e32 v0, 6, v44
	s_nop 0
	v_readfirstlane_b32 s4, v0
	s_cbranch_scc1 .LBB0_236
	s_sleep 64
	s_sub_i32 s3, s34, s2
	s_add_u32 s10, s22, 0x5400000
	s_addc_u32 s11, s23, 0
	s_ashr_i32 s6, s0, 7
	s_ashr_i32 s7, s6, 31
	s_lshl_b32 s1, s0, 4
	s_and_b32 s14, s0, 7
	s_lshl_b64 s[6:7], s[6:7], 11
	s_and_b32 s1, s1, 0x780
	s_lshl_b32 s15, s14, 14
	s_or_b32 s5, s6, s1
	v_cmp_gt_u32_e32 vcc, 0x80, v44
	s_nop 1
	v_cndmask_b32_e32 v216, 0, v44, vcc
	v_mov_b32_e32 v217, 0
	s_mov_b32 s98, s5
	s_mov_b32 s99, s7
	v_lshl_add_u64 v[218:219], s[98:99], 0, v[216:217]
	v_lshlrev_b64 v[218:219], 7, v[218:219]
	s_add_u32 s98, s22, 0xf800000
	s_addc_u32 s99, s23, 0
	v_lshl_add_u64 v[218:219], s[98:99], 0, v[218:219]
	global_load_dwordx4 v[168:171], v[218:219], off
	global_load_dwordx4 v[172:175], v[218:219], off offset:16
	global_load_dwordx4 v[176:179], v[218:219], off offset:32
	global_load_dwordx4 v[180:183], v[218:219], off offset:48
	global_load_dwordx4 v[184:187], v[218:219], off offset:64
	global_load_dwordx4 v[188:191], v[218:219], off offset:80
	global_load_dwordx4 v[192:195], v[218:219], off offset:96
	global_load_dwordx4 v[196:199], v[218:219], off offset:112
	s_or_b32 s0, s15, 0x60000
	v_ashrrev_i32_e32 v2, 3, v44
	v_lshlrev_b32_e32 v1, 1, v44
	v_and_b32_e32 v46, -8, v2
	s_add_u32 s0, s5, s0
	v_and_b32_e32 v1, 0x7e, v1
	v_ashrrev_i32_e32 v47, 31, v46
	s_addc_u32 s1, s7, 0
	v_lshl_add_u64 v[2:3], s[0:1], 0, v[46:47]
	v_lshlrev_b32_e32 v48, 1, v1
	v_mov_b32_e32 v49, 0
	v_lshl_add_u64 v[50:51], s[10:11], 0, v[48:49]
	v_lshlrev_b64 v[2:3], 8, v[2:3]
	v_lshl_add_u64 v[2:3], v[50:51], 0, v[2:3]
	s_movk_i32 s6, 0x4000
	s_bitset1_b32 s15, 18
	global_load_dword v62, v[2:3], off
	global_load_dword v63, v[2:3], off offset:256
	global_load_dword v64, v[2:3], off offset:512
	global_load_dword v65, v[2:3], off offset:768
	global_load_dword v66, v[2:3], off offset:1024
	global_load_dword v67, v[2:3], off offset:1280
	global_load_dword v68, v[2:3], off offset:1536
	global_load_dword v69, v[2:3], off offset:1792
	v_add_co_u32_e32 v2, vcc, s6, v2
	v_ashrrev_i32_e32 v52, 4, v44
	s_add_u32 s0, s5, s15
	v_addc_co_u32_e32 v3, vcc, 0, v3, vcc
	v_ashrrev_i32_e32 v53, 31, v52
	s_addc_u32 s1, s7, 0
	v_lshlrev_b32_e32 v4, 4, v44
	global_load_dword v70, v[2:3], off
	global_load_dword v71, v[2:3], off offset:256
	global_load_dword v72, v[2:3], off offset:512
	global_load_dword v73, v[2:3], off offset:768
	global_load_dword v74, v[2:3], off offset:1024
	global_load_dword v75, v[2:3], off offset:1280
	global_load_dword v76, v[2:3], off offset:1536
	global_load_dword v77, v[2:3], off offset:1792
	v_lshl_add_u64 v[2:3], s[0:1], 0, v[52:53]
	v_and_b32_e32 v48, 0xf0, v4
	v_lshl_add_u64 v[54:55], s[10:11], 0, v[48:49]
	v_lshlrev_b64 v[2:3], 8, v[2:3]
	v_lshl_add_u64 v[2:3], v[54:55], 0, v[2:3]
	s_movk_i32 s0, 0x2000
	v_add_co_u32_e32 v4, vcc, s0, v2
	s_movk_i32 s0, 0x6000
	s_nop 0
	v_addc_co_u32_e32 v5, vcc, 0, v3, vcc
	global_load_dwordx4 v[16:19], v[2:3], off
	global_load_dwordx4 v[20:23], v[4:5], off
	v_add_co_u32_e32 v4, vcc, s6, v2
	v_lshlrev_b32_e32 v78, 2, v1
	s_nop 0
	v_addc_co_u32_e32 v5, vcc, 0, v3, vcc
	v_add_co_u32_e32 v2, vcc, s0, v2
	v_lshl_or_b32 v1, s14, 9, v78
	s_nop 0
	v_addc_co_u32_e32 v3, vcc, 0, v3, vcc
	global_load_dwordx4 v[24:27], v[4:5], off
	global_load_dwordx4 v[28:31], v[2:3], off
	s_waitcnt lgkmcnt(0)
	global_load_dwordx2 v[58:59], v1, s[66:67]
	global_load_dwordx2 v[60:61], v1, s[8:9]
	v_and_b32_e32 v1, 63, v44
	v_bfe_u32 v5, v44, 5, 1
	s_movk_i32 s7, 0x220
	v_mad_u32_u24 v1, v1, s7, 0
	v_add_u32_e32 v6, 0, v48
	s_lshl_b32 s7, s4, 5
	v_lshlrev_b32_e32 v48, 4, v5
	s_lshl_b32 s4, s4, 4
	v_and_b32_e32 v4, 31, v44
	s_and_b32 s7, s7, 0x60
	v_lshl_add_u64 v[2:3], s[22:23], 0, v[48:49]
	s_mov_b64 s[10:11], 0x1100000
	s_andn2_b32 s4, s4, 63
	v_lshl_add_u64 v[56:57], v[2:3], 0, s[10:11]
	s_movk_i32 s10, 0x110
	v_or_b32_e32 v81, s7, v4
	v_or_b32_e32 v4, s4, v4
	s_add_i32 s5, 0, 0x11000
	v_mul_lo_u32 v10, v4, s10
	v_lshl_add_u32 v11, v4, 1, 0
	v_or_b32_e32 v4, 32, v4
	v_mul_lo_u32 v3, v52, s10
	v_mul_lo_u32 v12, v4, s10
	s_add_u32 s10, s22, 0xf800000
	s_addc_u32 s11, s23, 0
	s_lshl_b32 s4, s2, 1
	v_lshl_or_b32 v80, v5, 2, s7
	v_lshlrev_b32_e32 v7, 4, v0
	v_lshl_add_u32 v0, v0, 3, 64
	s_sub_i32 s7, s34, s4
	s_lshl_b32 s4, s34, 4
	s_lshl_b32 s14, s2, 5
	s_movk_i32 s0, 0x80
	v_add_u32_e32 v2, 0, v48
	v_and_b32_e32 v5, 0xffffffc0, v44
	v_lshlrev_b32_e32 v8, 3, v0
	v_lshlrev_b32_e32 v0, 1, v0
	v_mul_u32_u24_e32 v9, 0x110, v80
	v_lshl_add_u32 v4, v4, 1, 0
	s_sub_i32 s18, s4, s14
	s_lshl_b32 s14, s2, 4
	v_cmp_gt_i32_e64 s[0:1], s0, v44
	v_ashrrev_i32_e32 v45, 31, v44
	v_lshl_add_u32 v79, v44, 3, s5
	s_lshl_b32 s19, s24, 4
	s_sub_i32 s20, s4, s14
	s_sub_i32 s21, 0, s14
	s_sub_i32 s25, 0, s2
	s_mov_b32 s26, 0x3a800000
	s_mov_b32 s27, 0xf800000
	v_mov_b32_e32 v82, 0x260
	v_add_u32_e32 v83, v1, v7
	v_add_u32_e32 v84, v1, v0
	v_add_u32_e32 v85, v2, v10
	v_add_u32_e32 v86, v11, v9
	v_add_u32_e32 v87, v2, v12
	v_add_u32_e32 v88, v4, v9
	v_add_u32_e32 v89, s5, v5
	v_add_u32_e32 v90, s5, v8
	v_add_u32_e32 v91, v6, v3
	s_mov_b32 s28, s24
	s_waitcnt vmcnt(0)
	s_branch .LBB0_231
